# v037 with static s_setprio 3 (instead of 1) for waves 0-3
# speedup vs baseline: 1.0052x; 1.0052x over previous
; __device__ __forceinline__ int otid() { int t = threadIdx.x; asm volatile("" : "+v"(t)); return t; }
; template <class Epi>
; __device__ __forceinline__ void gemm_phase(LAS unsigned char* lds, const Gemm g, const StaticOrder& S, const Epi& E) {
;     const int tid = otid(), wid = __builtin_amdgcn_readfirstlane(tid >> 6), lane = tid & 63, wr = wid >> 2, wc = wid & 3, fr = lane & 15, fq = lane >> 4;
_Z8mega_fwd6Params:
	v_readfirstlane_b32 s101, v0
	s_and_b32 s101, s101, 0x3ff
	s_lshr_b32 s101, s101, 6
	s_cmp_lt_u32 s101, 4
	s_cbranch_scc0 .Lprio_done
	s_setprio 3
